# code placement: the five GEMM K-loop heads aligned to 64 bytes (.p2align 6)
# speedup vs baseline: 1.0219x; 1.0097x over previous
.LBB0_53:
	v_lshl_add_u32 v171, s48, 8, v241
	v_lshlrev_b32_e32 v171, 2, v171
	global_load_dword v164, v171, s[70:71]
	global_load_dword v165, v171, s[70:71] offset:64
	global_load_dword v166, v171, s[70:71] offset:128
	global_load_dword v167, v171, s[70:71] offset:192
	global_load_dword v246, v171, s[70:71] offset:512
	global_load_dword v247, v171, s[70:71] offset:576
	global_load_dword v248, v171, s[70:71] offset:640
	global_load_dword v249, v171, s[70:71] offset:704
	s_add_u32 s0, s4, 0x40080
	s_addc_u32 s1, s5, 0
	s_add_u32 s3, s20, 0x100
	v_mov_b32_e32 v4, 0
	s_addc_u32 s20, s21, 0
	s_mov_b32 s21, -2
	v_mov_b32_e32 v5, v4
	v_mov_b32_e32 v6, v4
	v_mov_b32_e32 v7, v4
	v_mov_b32_e32 v8, v4
	v_mov_b32_e32 v9, v4
	v_mov_b32_e32 v10, v4
	v_mov_b32_e32 v11, v4
	v_mov_b32_e32 v12, v4
	v_mov_b32_e32 v13, v4
	v_mov_b32_e32 v14, v4
	v_mov_b32_e32 v15, v4
	v_mov_b32_e32 v16, v4
	v_mov_b32_e32 v17, v4
	v_mov_b32_e32 v18, v4
	v_mov_b32_e32 v19, v4
	v_mov_b32_e32 v20, v4
	v_mov_b32_e32 v21, v4
	v_mov_b32_e32 v22, v4
	v_mov_b32_e32 v23, v4
	v_mov_b32_e32 v24, v4
	v_mov_b32_e32 v25, v4
	v_mov_b32_e32 v26, v4
	v_mov_b32_e32 v27, v4
	v_mov_b32_e32 v28, v4
	v_mov_b32_e32 v29, v4
	v_mov_b32_e32 v30, v4
	v_mov_b32_e32 v31, v4
	v_mov_b32_e32 v32, v4
	v_mov_b32_e32 v33, v4
	v_mov_b32_e32 v34, v4
	v_mov_b32_e32 v35, v4
	v_mov_b32_e32 v68, v4
	v_mov_b32_e32 v69, v4
	v_mov_b32_e32 v70, v4
	v_mov_b32_e32 v71, v4
	v_mov_b32_e32 v72, v4
	v_mov_b32_e32 v73, v4
	v_mov_b32_e32 v74, v4
	v_mov_b32_e32 v75, v4
	v_mov_b32_e32 v76, v4
	v_mov_b32_e32 v77, v4
	v_mov_b32_e32 v78, v4
	v_mov_b32_e32 v79, v4
	v_mov_b32_e32 v80, v4
	v_mov_b32_e32 v81, v4
	v_mov_b32_e32 v82, v4
	v_mov_b32_e32 v83, v4
	v_mov_b32_e32 v84, v4
	v_mov_b32_e32 v85, v4
	v_mov_b32_e32 v86, v4
	v_mov_b32_e32 v87, v4
	v_mov_b32_e32 v88, v4
	v_mov_b32_e32 v89, v4
	v_mov_b32_e32 v90, v4
	v_mov_b32_e32 v91, v4
	v_mov_b32_e32 v92, v4
	v_mov_b32_e32 v93, v4
	v_mov_b32_e32 v94, v4
	v_mov_b32_e32 v95, v4
	v_mov_b32_e32 v96, v4
	v_mov_b32_e32 v97, v4
	v_mov_b32_e32 v98, v4
	v_mov_b32_e32 v99, v4
	v_mov_b32_e32 v36, v4
	v_mov_b32_e32 v37, v4
	v_mov_b32_e32 v38, v4
	v_mov_b32_e32 v39, v4
	v_mov_b32_e32 v40, v4
	v_mov_b32_e32 v41, v4
	v_mov_b32_e32 v42, v4
	v_mov_b32_e32 v43, v4
	v_mov_b32_e32 v44, v4
	v_mov_b32_e32 v45, v4
	v_mov_b32_e32 v46, v4
	v_mov_b32_e32 v47, v4
	v_mov_b32_e32 v48, v4
	v_mov_b32_e32 v49, v4
	v_mov_b32_e32 v50, v4
	v_mov_b32_e32 v51, v4
	v_mov_b32_e32 v52, v4
	v_mov_b32_e32 v53, v4
	v_mov_b32_e32 v54, v4
	v_mov_b32_e32 v55, v4
	v_mov_b32_e32 v56, v4
	v_mov_b32_e32 v57, v4
	v_mov_b32_e32 v58, v4
	v_mov_b32_e32 v59, v4
	v_mov_b32_e32 v60, v4
	v_mov_b32_e32 v61, v4
	v_mov_b32_e32 v62, v4
	v_mov_b32_e32 v63, v4
	v_mov_b32_e32 v64, v4
	v_mov_b32_e32 v65, v4
	v_mov_b32_e32 v66, v4
	v_mov_b32_e32 v67, v4
	v_mov_b32_e32 v100, v4
	v_mov_b32_e32 v101, v4
	v_mov_b32_e32 v102, v4
	v_mov_b32_e32 v103, v4
	v_mov_b32_e32 v104, v4
	v_mov_b32_e32 v105, v4
	v_mov_b32_e32 v106, v4
	v_mov_b32_e32 v107, v4
	v_mov_b32_e32 v108, v4
	v_mov_b32_e32 v109, v4
	v_mov_b32_e32 v110, v4
	v_mov_b32_e32 v111, v4
	v_mov_b32_e32 v112, v4
	v_mov_b32_e32 v113, v4
	v_mov_b32_e32 v114, v4
	v_mov_b32_e32 v115, v4
	v_mov_b32_e32 v116, v4
	v_mov_b32_e32 v117, v4
	v_mov_b32_e32 v118, v4
	v_mov_b32_e32 v119, v4
	v_mov_b32_e32 v120, v4
	v_mov_b32_e32 v121, v4
	v_mov_b32_e32 v122, v4
	v_mov_b32_e32 v123, v4
	v_mov_b32_e32 v124, v4
	v_mov_b32_e32 v125, v4
	v_mov_b32_e32 v126, v4
	v_mov_b32_e32 v127, v4
	v_mov_b32_e32 v128, v4
	v_mov_b32_e32 v129, v4
	v_mov_b32_e32 v130, v4
	v_mov_b32_e32 v131, v4
	.p2align 6

.LBB0_631:
	s_add_i32 s48, s40, -2
	s_add_u32 s49, s4, 0x100
	s_addc_u32 s50, s5, 0
	s_mov_b32 s16, 0
	.p2align 6

.LBB0_839:
	s_add_u32 s10, s10, 0x40080
	s_addc_u32 s11, s11, 0
	s_add_u32 s1, s16, 0x100
	v_mov_b32_e32 v4, 0
	s_addc_u32 s3, s17, 0
	s_mov_b32 s44, -2
	v_mov_b32_e32 v5, v4
	v_mov_b32_e32 v6, v4
	v_mov_b32_e32 v7, v4
	v_mov_b32_e32 v8, v4
	v_mov_b32_e32 v9, v4
	v_mov_b32_e32 v10, v4
	v_mov_b32_e32 v11, v4
	v_mov_b32_e32 v12, v4
	v_mov_b32_e32 v13, v4
	v_mov_b32_e32 v14, v4
	v_mov_b32_e32 v15, v4
	v_mov_b32_e32 v16, v4
	v_mov_b32_e32 v17, v4
	v_mov_b32_e32 v18, v4
	v_mov_b32_e32 v19, v4
	v_mov_b32_e32 v20, v4
	v_mov_b32_e32 v21, v4
	v_mov_b32_e32 v22, v4
	v_mov_b32_e32 v23, v4
	v_mov_b32_e32 v24, v4
	v_mov_b32_e32 v25, v4
	v_mov_b32_e32 v26, v4
	v_mov_b32_e32 v27, v4
	v_mov_b32_e32 v28, v4
	v_mov_b32_e32 v29, v4
	v_mov_b32_e32 v30, v4
	v_mov_b32_e32 v31, v4
	v_mov_b32_e32 v32, v4
	v_mov_b32_e32 v33, v4
	v_mov_b32_e32 v34, v4
	v_mov_b32_e32 v35, v4
	v_mov_b32_e32 v40, v4
	v_mov_b32_e32 v41, v4
	v_mov_b32_e32 v42, v4
	v_mov_b32_e32 v43, v4
	v_mov_b32_e32 v48, v4
	v_mov_b32_e32 v49, v4
	v_mov_b32_e32 v50, v4
	v_mov_b32_e32 v51, v4
	v_mov_b32_e32 v60, v4
	v_mov_b32_e32 v61, v4
	v_mov_b32_e32 v62, v4
	v_mov_b32_e32 v63, v4
	v_mov_b32_e32 v64, v4
	v_mov_b32_e32 v65, v4
	v_mov_b32_e32 v66, v4
	v_mov_b32_e32 v67, v4
	v_mov_b32_e32 v80, v4
	v_mov_b32_e32 v81, v4
	v_mov_b32_e32 v82, v4
	v_mov_b32_e32 v83, v4
	v_mov_b32_e32 v88, v4
	v_mov_b32_e32 v89, v4
	v_mov_b32_e32 v90, v4
	v_mov_b32_e32 v91, v4
	v_mov_b32_e32 v92, v4
	v_mov_b32_e32 v93, v4
	v_mov_b32_e32 v94, v4
	v_mov_b32_e32 v95, v4
	v_mov_b32_e32 v96, v4
	v_mov_b32_e32 v97, v4
	v_mov_b32_e32 v98, v4
	v_mov_b32_e32 v99, v4
	v_mov_b32_e32 v36, v4
	v_mov_b32_e32 v37, v4
	v_mov_b32_e32 v38, v4
	v_mov_b32_e32 v39, v4
	v_mov_b32_e32 v44, v4
	v_mov_b32_e32 v45, v4
	v_mov_b32_e32 v46, v4
	v_mov_b32_e32 v47, v4
	v_mov_b32_e32 v52, v4
	v_mov_b32_e32 v53, v4
	v_mov_b32_e32 v54, v4
	v_mov_b32_e32 v55, v4
	v_mov_b32_e32 v56, v4
	v_mov_b32_e32 v57, v4
	v_mov_b32_e32 v58, v4
	v_mov_b32_e32 v59, v4
	v_mov_b32_e32 v68, v4
	v_mov_b32_e32 v69, v4
	v_mov_b32_e32 v70, v4
	v_mov_b32_e32 v71, v4
	v_mov_b32_e32 v72, v4
	v_mov_b32_e32 v73, v4
	v_mov_b32_e32 v74, v4
	v_mov_b32_e32 v75, v4
	v_mov_b32_e32 v76, v4
	v_mov_b32_e32 v77, v4
	v_mov_b32_e32 v78, v4
	v_mov_b32_e32 v79, v4
	v_mov_b32_e32 v84, v4
	v_mov_b32_e32 v85, v4
	v_mov_b32_e32 v86, v4
	v_mov_b32_e32 v87, v4
	v_mov_b32_e32 v100, v4
	v_mov_b32_e32 v101, v4
	v_mov_b32_e32 v102, v4
	v_mov_b32_e32 v103, v4
	v_mov_b32_e32 v104, v4
	v_mov_b32_e32 v105, v4
	v_mov_b32_e32 v106, v4
	v_mov_b32_e32 v107, v4
	v_mov_b32_e32 v108, v4
	v_mov_b32_e32 v109, v4
	v_mov_b32_e32 v110, v4
	v_mov_b32_e32 v111, v4
	v_mov_b32_e32 v112, v4
	v_mov_b32_e32 v113, v4
	v_mov_b32_e32 v114, v4
	v_mov_b32_e32 v115, v4
	v_mov_b32_e32 v116, v4
	v_mov_b32_e32 v117, v4
	v_mov_b32_e32 v118, v4
	v_mov_b32_e32 v119, v4
	v_mov_b32_e32 v120, v4
	v_mov_b32_e32 v121, v4
	v_mov_b32_e32 v122, v4
	v_mov_b32_e32 v123, v4
	v_mov_b32_e32 v124, v4
	v_mov_b32_e32 v125, v4
	v_mov_b32_e32 v126, v4
	v_mov_b32_e32 v127, v4
	v_mov_b32_e32 v128, v4
	v_mov_b32_e32 v129, v4
	v_mov_b32_e32 v130, v4
	v_mov_b32_e32 v131, v4
	.p2align 6

.LBB0_1097:
	s_add_u32 s2, s2, 0x40080
	s_addc_u32 s3, s3, 0
	s_add_u32 s9, s4, 0x100
	v_mov_b32_e32 v4, 0
	s_addc_u32 s11, s5, 0
	s_mov_b32 s53, -2
	v_mov_b32_e32 v5, v4
	v_mov_b32_e32 v6, v4
	v_mov_b32_e32 v7, v4
	v_mov_b32_e32 v8, v4
	v_mov_b32_e32 v9, v4
	v_mov_b32_e32 v10, v4
	v_mov_b32_e32 v11, v4
	v_mov_b32_e32 v12, v4
	v_mov_b32_e32 v13, v4
	v_mov_b32_e32 v14, v4
	v_mov_b32_e32 v15, v4
	v_mov_b32_e32 v16, v4
	v_mov_b32_e32 v17, v4
	v_mov_b32_e32 v18, v4
	v_mov_b32_e32 v19, v4
	v_mov_b32_e32 v20, v4
	v_mov_b32_e32 v21, v4
	v_mov_b32_e32 v22, v4
	v_mov_b32_e32 v23, v4
	v_mov_b32_e32 v24, v4
	v_mov_b32_e32 v25, v4
	v_mov_b32_e32 v26, v4
	v_mov_b32_e32 v27, v4
	v_mov_b32_e32 v28, v4
	v_mov_b32_e32 v29, v4
	v_mov_b32_e32 v30, v4
	v_mov_b32_e32 v31, v4
	v_mov_b32_e32 v32, v4
	v_mov_b32_e32 v33, v4
	v_mov_b32_e32 v34, v4
	v_mov_b32_e32 v35, v4
	v_mov_b32_e32 v60, v4
	v_mov_b32_e32 v61, v4
	v_mov_b32_e32 v62, v4
	v_mov_b32_e32 v63, v4
	v_mov_b32_e32 v64, v4
	v_mov_b32_e32 v65, v4
	v_mov_b32_e32 v66, v4
	v_mov_b32_e32 v67, v4
	v_mov_b32_e32 v76, v4
	v_mov_b32_e32 v77, v4
	v_mov_b32_e32 v78, v4
	v_mov_b32_e32 v79, v4
	v_mov_b32_e32 v80, v4
	v_mov_b32_e32 v81, v4
	v_mov_b32_e32 v82, v4
	v_mov_b32_e32 v83, v4
	v_mov_b32_e32 v84, v4
	v_mov_b32_e32 v85, v4
	v_mov_b32_e32 v86, v4
	v_mov_b32_e32 v87, v4
	v_mov_b32_e32 v88, v4
	v_mov_b32_e32 v89, v4
	v_mov_b32_e32 v90, v4
	v_mov_b32_e32 v91, v4
	v_mov_b32_e32 v92, v4
	v_mov_b32_e32 v93, v4
	v_mov_b32_e32 v94, v4
	v_mov_b32_e32 v95, v4
	v_mov_b32_e32 v96, v4
	v_mov_b32_e32 v97, v4
	v_mov_b32_e32 v98, v4
	v_mov_b32_e32 v99, v4
	v_mov_b32_e32 v36, v4
	v_mov_b32_e32 v37, v4
	v_mov_b32_e32 v38, v4
	v_mov_b32_e32 v39, v4
	v_mov_b32_e32 v40, v4
	v_mov_b32_e32 v41, v4
	v_mov_b32_e32 v42, v4
	v_mov_b32_e32 v43, v4
	v_mov_b32_e32 v44, v4
	v_mov_b32_e32 v45, v4
	v_mov_b32_e32 v46, v4
	v_mov_b32_e32 v47, v4
	v_mov_b32_e32 v48, v4
	v_mov_b32_e32 v49, v4
	v_mov_b32_e32 v50, v4
	v_mov_b32_e32 v51, v4
	v_mov_b32_e32 v52, v4
	v_mov_b32_e32 v53, v4
	v_mov_b32_e32 v54, v4
	v_mov_b32_e32 v55, v4
	v_mov_b32_e32 v56, v4
	v_mov_b32_e32 v57, v4
	v_mov_b32_e32 v58, v4
	v_mov_b32_e32 v59, v4
	v_mov_b32_e32 v68, v4
	v_mov_b32_e32 v69, v4
	v_mov_b32_e32 v70, v4
	v_mov_b32_e32 v71, v4
	v_mov_b32_e32 v72, v4
	v_mov_b32_e32 v73, v4
	v_mov_b32_e32 v74, v4
	v_mov_b32_e32 v75, v4
	v_mov_b32_e32 v100, v4
	v_mov_b32_e32 v101, v4
	v_mov_b32_e32 v102, v4
	v_mov_b32_e32 v103, v4
	v_mov_b32_e32 v104, v4
	v_mov_b32_e32 v105, v4
	v_mov_b32_e32 v106, v4
	v_mov_b32_e32 v107, v4
	v_mov_b32_e32 v108, v4
	v_mov_b32_e32 v109, v4
	v_mov_b32_e32 v110, v4
	v_mov_b32_e32 v111, v4
	v_mov_b32_e32 v112, v4
	v_mov_b32_e32 v113, v4
	v_mov_b32_e32 v114, v4
	v_mov_b32_e32 v115, v4
	v_mov_b32_e32 v116, v4
	v_mov_b32_e32 v117, v4
	v_mov_b32_e32 v118, v4
	v_mov_b32_e32 v119, v4
	v_mov_b32_e32 v120, v4
	v_mov_b32_e32 v121, v4
	v_mov_b32_e32 v122, v4
	v_mov_b32_e32 v123, v4
	v_mov_b32_e32 v124, v4
	v_mov_b32_e32 v125, v4
	v_mov_b32_e32 v126, v4
	v_mov_b32_e32 v127, v4
	v_mov_b32_e32 v128, v4
	v_mov_b32_e32 v129, v4
	v_mov_b32_e32 v130, v4
	v_mov_b32_e32 v131, v4
	v_lshl_add_u32 v171, s37, 8, v156
	v_lshlrev_b32_e32 v171, 2, v171
	global_load_dword v164, v171, s[70:71]
	global_load_dword v165, v171, s[70:71] offset:64
	global_load_dword v166, v171, s[70:71] offset:128
	global_load_dword v167, v171, s[70:71] offset:192
	global_load_dword v246, v171, s[70:71] offset:512
	global_load_dword v247, v171, s[70:71] offset:576
	global_load_dword v248, v171, s[70:71] offset:640
	global_load_dword v249, v171, s[70:71] offset:704
	.p2align 6

.LBB0_1174:
	s_add_u32 s20, s20, 0x100080
	s_addc_u32 s21, s21, 0
	s_add_u32 s3, s16, 0x100
	v_mov_b32_e32 v4, 0
	s_addc_u32 s5, s17, 0
	s_mov_b32 s48, -2
	v_mov_b32_e32 v5, v4
	v_mov_b32_e32 v6, v4
	v_mov_b32_e32 v7, v4
	v_mov_b32_e32 v8, v4
	v_mov_b32_e32 v9, v4
	v_mov_b32_e32 v10, v4
	v_mov_b32_e32 v11, v4
	v_mov_b32_e32 v12, v4
	v_mov_b32_e32 v13, v4
	v_mov_b32_e32 v14, v4
	v_mov_b32_e32 v15, v4
	v_mov_b32_e32 v16, v4
	v_mov_b32_e32 v17, v4
	v_mov_b32_e32 v18, v4
	v_mov_b32_e32 v19, v4
	v_mov_b32_e32 v20, v4
	v_mov_b32_e32 v21, v4
	v_mov_b32_e32 v22, v4
	v_mov_b32_e32 v23, v4
	v_mov_b32_e32 v24, v4
	v_mov_b32_e32 v25, v4
	v_mov_b32_e32 v26, v4
	v_mov_b32_e32 v27, v4
	v_mov_b32_e32 v28, v4
	v_mov_b32_e32 v29, v4
	v_mov_b32_e32 v30, v4
	v_mov_b32_e32 v31, v4
	v_mov_b32_e32 v32, v4
	v_mov_b32_e32 v33, v4
	v_mov_b32_e32 v34, v4
	v_mov_b32_e32 v35, v4
	v_mov_b32_e32 v40, v4
	v_mov_b32_e32 v41, v4
	v_mov_b32_e32 v42, v4
	v_mov_b32_e32 v43, v4
	v_mov_b32_e32 v48, v4
	v_mov_b32_e32 v49, v4
	v_mov_b32_e32 v50, v4
	v_mov_b32_e32 v51, v4
	v_mov_b32_e32 v60, v4
	v_mov_b32_e32 v61, v4
	v_mov_b32_e32 v62, v4
	v_mov_b32_e32 v63, v4
	v_mov_b32_e32 v64, v4
	v_mov_b32_e32 v65, v4
	v_mov_b32_e32 v66, v4
	v_mov_b32_e32 v67, v4
	v_mov_b32_e32 v80, v4
	v_mov_b32_e32 v81, v4
	v_mov_b32_e32 v82, v4
	v_mov_b32_e32 v83, v4
	v_mov_b32_e32 v88, v4
	v_mov_b32_e32 v89, v4
	v_mov_b32_e32 v90, v4
	v_mov_b32_e32 v91, v4
	v_mov_b32_e32 v92, v4
	v_mov_b32_e32 v93, v4
	v_mov_b32_e32 v94, v4
	v_mov_b32_e32 v95, v4
	v_mov_b32_e32 v96, v4
	v_mov_b32_e32 v97, v4
	v_mov_b32_e32 v98, v4
	v_mov_b32_e32 v99, v4
	v_mov_b32_e32 v36, v4
	v_mov_b32_e32 v37, v4
	v_mov_b32_e32 v38, v4
	v_mov_b32_e32 v39, v4
	v_mov_b32_e32 v44, v4
	v_mov_b32_e32 v45, v4
	v_mov_b32_e32 v46, v4
	v_mov_b32_e32 v47, v4
	v_mov_b32_e32 v52, v4
	v_mov_b32_e32 v53, v4
	v_mov_b32_e32 v54, v4
	v_mov_b32_e32 v55, v4
	v_mov_b32_e32 v56, v4
	v_mov_b32_e32 v57, v4
	v_mov_b32_e32 v58, v4
	v_mov_b32_e32 v59, v4
	v_mov_b32_e32 v68, v4
	v_mov_b32_e32 v69, v4
	v_mov_b32_e32 v70, v4
	v_mov_b32_e32 v71, v4
	v_mov_b32_e32 v72, v4
	v_mov_b32_e32 v73, v4
	v_mov_b32_e32 v74, v4
	v_mov_b32_e32 v75, v4
	v_mov_b32_e32 v76, v4
	v_mov_b32_e32 v77, v4
	v_mov_b32_e32 v78, v4
	v_mov_b32_e32 v79, v4
	v_mov_b32_e32 v84, v4
	v_mov_b32_e32 v85, v4
	v_mov_b32_e32 v86, v4
	v_mov_b32_e32 v87, v4
	v_mov_b32_e32 v100, v4
	v_mov_b32_e32 v101, v4
	v_mov_b32_e32 v102, v4
	v_mov_b32_e32 v103, v4
	v_mov_b32_e32 v104, v4
	v_mov_b32_e32 v105, v4
	v_mov_b32_e32 v106, v4
	v_mov_b32_e32 v107, v4
	v_mov_b32_e32 v108, v4
	v_mov_b32_e32 v109, v4
	v_mov_b32_e32 v110, v4
	v_mov_b32_e32 v111, v4
	v_mov_b32_e32 v112, v4
	v_mov_b32_e32 v113, v4
	v_mov_b32_e32 v114, v4
	v_mov_b32_e32 v115, v4
	v_mov_b32_e32 v116, v4
	v_mov_b32_e32 v117, v4
	v_mov_b32_e32 v118, v4
	v_mov_b32_e32 v119, v4
	v_mov_b32_e32 v120, v4
	v_mov_b32_e32 v121, v4
	v_mov_b32_e32 v122, v4
	v_mov_b32_e32 v123, v4
	v_mov_b32_e32 v124, v4
	v_mov_b32_e32 v125, v4
	v_mov_b32_e32 v126, v4
	v_mov_b32_e32 v127, v4
	v_mov_b32_e32 v128, v4
	v_mov_b32_e32 v129, v4
	v_mov_b32_e32 v130, v4
	v_mov_b32_e32 v131, v4
	.p2align 6
